# scan step: S^T fragment reads issued before the step's prefetch memory instructions; attention item: norm-weight load not serialised (both halves of the scan phase)
# speedup vs baseline: 1.0073x; 1.0047x over previous
.LBB0_469:
	s_waitcnt vmcnt(1)
	v_mov_b64_e32 v[92:93], v[16:17]
	v_mov_b64_e32 v[94:95], v[18:19]
	v_mov_b64_e32 v[88:89], v[20:21]
	v_mov_b64_e32 v[90:91], v[22:23]
	v_mov_b64_e32 v[120:121], v[104:105]
	v_mov_b64_e32 v[118:119], v[102:103]
	v_mov_b32_e32 v116, v100
	ds_read_b128 v[148:151], v200
	ds_read_b128 v[126:129], v200 offset:16384
	ds_read_b128 v[170:173], v201
	ds_read_b128 v[130:133], v201 offset:16384
	ds_read_b128 v[174:177], v202
	ds_read_b128 v[140:143], v202 offset:16384
	ds_read_b128 v[178:181], v203
	ds_read_b128 v[144:147], v203 offset:16384
	ds_read_b128 v[84:87], v208 offset:32768
	ds_read_b128 v[80:83], v208 offset:34816
	ds_read_b128 v[76:79], v209 offset:32768
	ds_read_b128 v[72:75], v209 offset:34816
	ds_read_b128 v[182:185], v124
	ds_read_b128 v[190:193], v124 offset:4352
	s_add_u32 m0, s36, 0x16800
	s_nop 0
	global_load_lds_dwordx4 v194, s[38:39]
	s_add_u32 m0, s36, 0x16c00
	s_nop 0
	global_load_lds_dwordx4 v195, s[38:39]
	s_add_u32 m0, s36, 0x1a800
	s_nop 0
	global_load_lds_dwordx4 v196, s[38:39]
	s_add_u32 m0, s36, 0x1ac00
	s_nop 0
	global_load_lds_dwordx4 v197, s[38:39]
	s_add_u32 m0, s36, 0x1e800
	s_nop 0
	global_load_lds_dwordx4 v198, s[38:39]
	s_add_u32 m0, s36, 0x1ec00
	s_nop 0
	global_load_lds_dwordx4 v199, s[38:39]
	s_add_u32 s38, s38, 0x4000
	s_addc_u32 s39, s39, 0
	v_lshl_add_u64 v[0:1], s[72:73], 0, v[110:111]
	s_mov_b32 s7, 0x23502000
	v_add_co_u32_e32 v0, vcc, s7, v0
	s_nop 1
	v_addc_co_u32_e32 v1, vcc, 0, v1, vcc
	global_load_dwordx4 v[16:19], v[0:1], off
	global_load_dwordx4 v[20:23], v[0:1], off offset:64
	v_lshl_add_u64 v[102:103], s[72:73], 0, v[108:109]
	s_mov_b32 s7, 0x1d504000
	v_add_co_u32_e32 v102, vcc, s7, v102
	s_add_u32 s8, s72, s1
	s_nop 0
	v_addc_co_u32_e32 v103, vcc, 0, v103, vcc
	s_addc_u32 s9, s73, s11
	global_load_dwordx2 v[104:105], v[102:103], off
	s_nop 0
	global_load_dwordx2 v[102:103], v[102:103], off offset:2048
	global_load_dword v100, v137, s[8:9]
	s_waitcnt lgkmcnt(1)
	v_mfma_f32_16x16x32_bf16 v[186:189], v[148:151], v[182:185], 0
	v_lshlrev_b32_e32 v134, 16, v120
	v_and_b32_e32 v135, 0xffff0000, v120
	v_lshlrev_b32_e32 v120, 16, v121
	v_mfma_f32_16x16x32_bf16 v[182:185], v[126:129], v[182:185], 0
	v_and_b32_e32 v121, 0xffff0000, v121
	v_pk_mul_f32 v[70:71], v[70:71], v[116:117] op_sel_hi:[1,0]
	v_pk_mul_f32 v[68:69], v[68:69], v[116:117] op_sel_hi:[1,0]
	s_waitcnt lgkmcnt(0)
	v_mfma_f32_16x16x32_bf16 v[148:151], v[148:151], v[190:193], 0
	v_mul_f32_e64 v58, v58, v116
	v_mul_f32_e64 v59, v59, v116
	v_pk_mul_f32 v[56:57], v[56:57], v[116:117] op_sel_hi:[1,0]
	v_pk_mul_f32 v[62:63], v[62:63], v[116:117] op_sel_hi:[1,0]
	v_mfma_f32_16x16x32_bf16 v[126:129], v[126:129], v[190:193], 0
	ds_read_b128 v[190:193], v124 offset:64
	v_pk_mul_f32 v[60:61], v[60:61], v[116:117] op_sel_hi:[1,0]
	v_pk_mul_f32 v[38:39], v[38:39], v[116:117] op_sel_hi:[1,0]
	s_waitcnt lgkmcnt(0)
	v_mfma_f32_16x16x32_bf16 v[186:189], v[170:173], v[190:193], v[186:189]
	v_mul_f32_e64 v36, v36, v116
	v_mul_f32_e64 v37, v37, v116
	s_add_i32 s6, s6, -1
	s_add_u32 s1, s1, 4
	v_mfma_f32_16x16x32_bf16 v[182:185], v[130:133], v[190:193], v[182:185]
	ds_read_b128 v[190:193], v124 offset:4416
	s_addc_u32 s11, s11, 0
	v_lshl_add_u64 v[108:109], v[108:109], 0, s[26:27]
	s_waitcnt lgkmcnt(0)
	v_mfma_f32_16x16x32_bf16 v[126:129], v[130:133], v[190:193], v[126:129]
	ds_read_b128 v[130:133], v124 offset:128
	v_lshl_add_u64 v[110:111], v[110:111], 0, s[14:15]
	v_lshl_add_u64 v[112:113], v[112:113], 0, s[26:27]
	v_mfma_f32_16x16x32_bf16 v[148:151], v[170:173], v[190:193], v[148:151]
	v_lshl_add_u64 v[114:115], v[114:115], 0, s[26:27]
	s_cmp_lg_u32 s6, 0
	s_waitcnt lgkmcnt(0)
	v_mfma_f32_16x16x32_bf16 v[170:173], v[174:177], v[130:133], v[186:189]
	v_mfma_f32_16x16x32_bf16 v[130:133], v[140:143], v[130:133], v[182:185]
	s_nop 2
	ds_read_b128 v[182:185], v124 offset:4480
	s_waitcnt lgkmcnt(0)
	v_mfma_f32_16x16x32_bf16 v[126:129], v[140:143], v[182:185], v[126:129]
	ds_read_b128 v[140:143], v124 offset:192
	s_waitcnt lgkmcnt(0)
	v_mfma_f32_16x16x32_bf16 v[170:173], v[178:181], v[140:143], v[170:173]
	v_mfma_f32_16x16x32_bf16 v[130:133], v[144:147], v[140:143], v[130:133]
	ds_read_b128 v[140:143], v124 offset:4544
	s_nop 5
	v_pk_add_f32 v[134:135], v[134:135], v[170:171] neg_lo:[0,1] neg_hi:[0,1]
	v_pk_add_f32 v[120:121], v[120:121], v[172:173] neg_lo:[0,1] neg_hi:[0,1]
	v_mfma_f32_16x16x32_bf16 v[148:151], v[174:177], v[182:185], v[148:151]
	v_cvt_pk_bf16_f32 v134, v134, v135
	v_cvt_pk_bf16_f32 v135, v120, v121
	v_lshlrev_b32_e32 v120, 16, v118
	s_waitcnt lgkmcnt(0)
	v_mfma_f32_16x16x32_bf16 v[148:151], v[178:181], v[140:143], v[148:151]
	v_and_b32_e32 v121, 0xffff0000, v118
	v_lshlrev_b32_e32 v118, 16, v119
	v_and_b32_e32 v119, 0xffff0000, v119
	ds_write_b64 v117, v[134:135] offset:8704
	v_mfma_f32_16x16x32_bf16 v[126:129], v[144:147], v[140:143], v[126:129]
	s_nop 2
	v_add_f32_e64 v120, v120, -v148
	v_add_f32_e64 v121, v121, -v149
	v_pk_add_f32 v[118:119], v[118:119], v[150:151] neg_lo:[0,1] neg_hi:[0,1]
	v_cvt_pk_bf16_f32 v120, v120, v121
	v_cvt_pk_bf16_f32 v121, v118, v119
	ds_write_b64 v117, v[120:121] offset:11008
	s_waitcnt lgkmcnt(0)
	s_barrier
	ds_read_b128 v[118:121], v122 offset:8704
	ds_read_b128 v[140:143], v123 offset:13056
	ds_read_b128 v[144:147], v122 offset:8768
	ds_read_b128 v[148:151], v123 offset:13120
	s_waitcnt lgkmcnt(3)
	v_mfma_f32_16x16x32_bf16 v[130:133], v[92:95], v[118:121], v[130:133]
	s_waitcnt lgkmcnt(2)
	v_mfma_f32_16x16x32_bf16 v[92:95], v[92:95], v[140:143], v[126:129]
	v_mfma_f32_16x16x32_bf16 v[68:71], v[84:87], v[118:121], v[68:71]
	v_mfma_f32_16x16x32_bf16 v[56:59], v[80:83], v[118:121], v[56:59]
	s_waitcnt lgkmcnt(1)
	v_mfma_f32_16x16x32_bf16 v[126:129], v[88:91], v[144:147], v[130:133]
	s_waitcnt lgkmcnt(0)
	v_mfma_f32_16x16x32_bf16 v[88:91], v[88:91], v[148:151], v[92:95]
	v_mfma_f32_16x16x32_bf16 v[60:63], v[84:87], v[140:143], v[60:63]
	s_nop 4
	v_cvt_pk_bf16_f32 v92, v126, s0
	s_nop 0
	v_cvt_pk_bf16_f32 v88, v88, s0
	ds_write_b16 v101, v92 offset:13312
	v_mfma_f32_16x16x32_bf16 v[36:39], v[80:83], v[140:143], v[36:39]
	v_cvt_pk_bf16_f32 v92, v127, s0
	ds_write_b16 v101, v88 offset:13344
	v_cvt_pk_bf16_f32 v88, v89, s0
	v_mfma_f32_16x16x32_bf16 v[68:71], v[76:79], v[144:147], v[68:71]
	ds_write_b16 v101, v92 offset:13392
	v_cvt_pk_bf16_f32 v92, v128, s0
	ds_write_b16 v101, v88 offset:13424
	v_mfma_f32_16x16x32_bf16 v[56:59], v[72:75], v[144:147], v[56:59]
	v_cvt_pk_bf16_f32 v88, v90, s0
	ds_write_b16 v101, v92 offset:13472
	v_cvt_pk_bf16_f32 v92, v129, s0
	v_mfma_f32_16x16x32_bf16 v[60:63], v[76:79], v[148:151], v[60:63]
	ds_write_b16 v101, v88 offset:13504
	v_cvt_pk_bf16_f32 v88, v91, s0
	s_nop 1
	v_cvt_pk_bf16_f32 v76, v56, v57
	v_mfma_f32_16x16x32_bf16 v[36:39], v[72:75], v[148:151], v[36:39]
	v_cvt_pk_bf16_f32 v72, v68, v69
	v_cvt_pk_bf16_f32 v73, v70, v71
	v_cvt_pk_bf16_f32 v77, v58, v59
	ds_write_b16 v101, v92 offset:13552
	ds_write_b16 v101, v88 offset:13584
	v_cvt_pk_bf16_f32 v74, v60, v61
	v_cvt_pk_bf16_f32 v75, v62, v63
	ds_write2_b64 v99, v[72:73], v[76:77] offset1:4
	v_cvt_pk_bf16_f32 v76, v36, v37
	v_cvt_pk_bf16_f32 v77, v38, v39
	v_add_u32_e32 v72, 0x1000, v99
	ds_write2_b64 v72, v[74:75], v[76:77] offset0:32 offset1:36
	s_waitcnt lgkmcnt(0)
	s_waitcnt vmcnt(5)
	s_barrier
	ds_read_b128 v[74:77], v97 offset:13312
	v_lshl_add_u64 v[78:79], s[72:73], 0, v[106:107]
	v_lshl_add_u64 v[106:107], v[106:107], 0, s[12:13]
	s_waitcnt lgkmcnt(0)
	global_store_dwordx4 v[78:79], v[74:77], off
	s_waitcnt vmcnt(1)
	v_mov_b64_e32 v[92:93], v[16:17]
	v_mov_b64_e32 v[94:95], v[18:19]
	v_mov_b64_e32 v[88:89], v[20:21]
	v_mov_b64_e32 v[90:91], v[22:23]
	v_mov_b64_e32 v[120:121], v[104:105]
	v_mov_b64_e32 v[118:119], v[102:103]
	v_mov_b32_e32 v116, v100
	ds_read_b128 v[148:151], v204
	ds_read_b128 v[126:129], v204 offset:16384
	ds_read_b128 v[170:173], v205
	ds_read_b128 v[130:133], v205 offset:16384
	ds_read_b128 v[174:177], v206
	ds_read_b128 v[140:143], v206 offset:16384
	ds_read_b128 v[178:181], v207
	ds_read_b128 v[144:147], v207 offset:16384
	ds_read_b128 v[84:87], v210 offset:32768
	ds_read_b128 v[80:83], v210 offset:34816
	ds_read_b128 v[76:79], v211 offset:32768
	ds_read_b128 v[72:75], v211 offset:34816
	ds_read_b128 v[182:185], v124
	ds_read_b128 v[190:193], v124 offset:4352
	s_add_u32 m0, s36, 0x4800
	s_nop 0
	global_load_lds_dwordx4 v194, s[38:39]
	s_add_u32 m0, s36, 0x4c00
	s_nop 0
	global_load_lds_dwordx4 v195, s[38:39]
	s_add_u32 m0, s36, 0x8800
	s_nop 0
	global_load_lds_dwordx4 v196, s[38:39]
	s_add_u32 m0, s36, 0x8c00
	s_nop 0
	global_load_lds_dwordx4 v197, s[38:39]
	s_add_u32 m0, s36, 0xc800
	s_nop 0
	global_load_lds_dwordx4 v198, s[38:39]
	s_add_u32 m0, s36, 0xcc00
	s_nop 0
	global_load_lds_dwordx4 v199, s[38:39]
	s_add_u32 s38, s38, 0x4000
	s_addc_u32 s39, s39, 0
	v_lshl_add_u64 v[0:1], s[72:73], 0, v[110:111]
	s_mov_b32 s7, 0x23502000
	v_add_co_u32_e32 v0, vcc, s7, v0
	s_nop 1
	v_addc_co_u32_e32 v1, vcc, 0, v1, vcc
	global_load_dwordx4 v[16:19], v[0:1], off
	global_load_dwordx4 v[20:23], v[0:1], off offset:64
	v_lshl_add_u64 v[102:103], s[72:73], 0, v[108:109]
	s_mov_b32 s7, 0x1d504000
	v_add_co_u32_e32 v102, vcc, s7, v102
	s_add_u32 s8, s72, s1
	s_nop 0
	v_addc_co_u32_e32 v103, vcc, 0, v103, vcc
	s_addc_u32 s9, s73, s11
	global_load_dwordx2 v[104:105], v[102:103], off
	s_nop 0
	global_load_dwordx2 v[102:103], v[102:103], off offset:2048
	global_load_dword v100, v137, s[8:9]
	s_waitcnt lgkmcnt(1)
	v_mfma_f32_16x16x32_bf16 v[186:189], v[148:151], v[182:185], 0
	v_lshlrev_b32_e32 v134, 16, v120
	v_and_b32_e32 v135, 0xffff0000, v120
	v_lshlrev_b32_e32 v120, 16, v121
	v_mfma_f32_16x16x32_bf16 v[182:185], v[126:129], v[182:185], 0
	v_and_b32_e32 v121, 0xffff0000, v121
	v_pk_mul_f32 v[70:71], v[70:71], v[116:117] op_sel_hi:[1,0]
	v_pk_mul_f32 v[68:69], v[68:69], v[116:117] op_sel_hi:[1,0]
	s_waitcnt lgkmcnt(0)
	v_mfma_f32_16x16x32_bf16 v[148:151], v[148:151], v[190:193], 0
	v_mul_f32_e64 v58, v58, v116
	v_mul_f32_e64 v59, v59, v116
	v_pk_mul_f32 v[56:57], v[56:57], v[116:117] op_sel_hi:[1,0]
	v_pk_mul_f32 v[62:63], v[62:63], v[116:117] op_sel_hi:[1,0]
	v_mfma_f32_16x16x32_bf16 v[126:129], v[126:129], v[190:193], 0
	ds_read_b128 v[190:193], v124 offset:64
	v_pk_mul_f32 v[60:61], v[60:61], v[116:117] op_sel_hi:[1,0]
	v_pk_mul_f32 v[38:39], v[38:39], v[116:117] op_sel_hi:[1,0]
	s_waitcnt lgkmcnt(0)
	v_mfma_f32_16x16x32_bf16 v[186:189], v[170:173], v[190:193], v[186:189]
	v_mul_f32_e64 v36, v36, v116
	v_mul_f32_e64 v37, v37, v116
	s_add_i32 s6, s6, -1
	s_add_u32 s1, s1, 4
	v_mfma_f32_16x16x32_bf16 v[182:185], v[130:133], v[190:193], v[182:185]
	ds_read_b128 v[190:193], v124 offset:4416
	s_addc_u32 s11, s11, 0
	v_lshl_add_u64 v[108:109], v[108:109], 0, s[26:27]
	s_waitcnt lgkmcnt(0)
	v_mfma_f32_16x16x32_bf16 v[126:129], v[130:133], v[190:193], v[126:129]
	ds_read_b128 v[130:133], v124 offset:128
	v_lshl_add_u64 v[110:111], v[110:111], 0, s[14:15]
	v_lshl_add_u64 v[112:113], v[112:113], 0, s[26:27]
	v_mfma_f32_16x16x32_bf16 v[148:151], v[170:173], v[190:193], v[148:151]
	v_lshl_add_u64 v[114:115], v[114:115], 0, s[26:27]
	s_cmp_lg_u32 s6, 0
	s_waitcnt lgkmcnt(0)
	v_mfma_f32_16x16x32_bf16 v[170:173], v[174:177], v[130:133], v[186:189]
	v_mfma_f32_16x16x32_bf16 v[130:133], v[140:143], v[130:133], v[182:185]
	s_nop 2
	ds_read_b128 v[182:185], v124 offset:4480
	s_waitcnt lgkmcnt(0)
	v_mfma_f32_16x16x32_bf16 v[126:129], v[140:143], v[182:185], v[126:129]
	ds_read_b128 v[140:143], v124 offset:192
	s_waitcnt lgkmcnt(0)
	v_mfma_f32_16x16x32_bf16 v[170:173], v[178:181], v[140:143], v[170:173]
	v_mfma_f32_16x16x32_bf16 v[130:133], v[144:147], v[140:143], v[130:133]
	ds_read_b128 v[140:143], v124 offset:4544
	s_nop 5
	v_pk_add_f32 v[134:135], v[134:135], v[170:171] neg_lo:[0,1] neg_hi:[0,1]
	v_pk_add_f32 v[120:121], v[120:121], v[172:173] neg_lo:[0,1] neg_hi:[0,1]
	v_mfma_f32_16x16x32_bf16 v[148:151], v[174:177], v[182:185], v[148:151]
	v_cvt_pk_bf16_f32 v134, v134, v135
	v_cvt_pk_bf16_f32 v135, v120, v121
	v_lshlrev_b32_e32 v120, 16, v118
	s_waitcnt lgkmcnt(0)
	v_mfma_f32_16x16x32_bf16 v[148:151], v[178:181], v[140:143], v[148:151]
	v_and_b32_e32 v121, 0xffff0000, v118
	v_lshlrev_b32_e32 v118, 16, v119
	v_and_b32_e32 v119, 0xffff0000, v119
	ds_write_b64 v117, v[134:135] offset:8704
	v_mfma_f32_16x16x32_bf16 v[126:129], v[144:147], v[140:143], v[126:129]
	s_nop 2
	v_add_f32_e64 v120, v120, -v148
	v_add_f32_e64 v121, v121, -v149
	v_pk_add_f32 v[118:119], v[118:119], v[150:151] neg_lo:[0,1] neg_hi:[0,1]
	v_cvt_pk_bf16_f32 v120, v120, v121
	v_cvt_pk_bf16_f32 v121, v118, v119
	ds_write_b64 v117, v[120:121] offset:11008
	s_waitcnt lgkmcnt(0)
	s_barrier
	ds_read_b128 v[118:121], v122 offset:8704
	ds_read_b128 v[140:143], v123 offset:13056
	ds_read_b128 v[144:147], v122 offset:8768
	ds_read_b128 v[148:151], v123 offset:13120
	s_waitcnt lgkmcnt(3)
	v_mfma_f32_16x16x32_bf16 v[130:133], v[92:95], v[118:121], v[130:133]
	s_waitcnt lgkmcnt(2)
	v_mfma_f32_16x16x32_bf16 v[92:95], v[92:95], v[140:143], v[126:129]
	v_mfma_f32_16x16x32_bf16 v[68:71], v[84:87], v[118:121], v[68:71]
	v_mfma_f32_16x16x32_bf16 v[56:59], v[80:83], v[118:121], v[56:59]
	s_waitcnt lgkmcnt(1)
	v_mfma_f32_16x16x32_bf16 v[126:129], v[88:91], v[144:147], v[130:133]
	s_waitcnt lgkmcnt(0)
	v_mfma_f32_16x16x32_bf16 v[88:91], v[88:91], v[148:151], v[92:95]
	v_mfma_f32_16x16x32_bf16 v[60:63], v[84:87], v[140:143], v[60:63]
	s_nop 4
	v_cvt_pk_bf16_f32 v92, v126, s0
	s_nop 0
	v_cvt_pk_bf16_f32 v88, v88, s0
	ds_write_b16 v101, v92 offset:13312
	v_mfma_f32_16x16x32_bf16 v[36:39], v[80:83], v[140:143], v[36:39]
	v_cvt_pk_bf16_f32 v92, v127, s0
	ds_write_b16 v101, v88 offset:13344
	v_cvt_pk_bf16_f32 v88, v89, s0
	v_mfma_f32_16x16x32_bf16 v[68:71], v[76:79], v[144:147], v[68:71]
	ds_write_b16 v101, v92 offset:13392
	v_cvt_pk_bf16_f32 v92, v128, s0
	ds_write_b16 v101, v88 offset:13424
	v_mfma_f32_16x16x32_bf16 v[56:59], v[72:75], v[144:147], v[56:59]
	v_cvt_pk_bf16_f32 v88, v90, s0
	ds_write_b16 v101, v92 offset:13472
	v_cvt_pk_bf16_f32 v92, v129, s0
	v_mfma_f32_16x16x32_bf16 v[60:63], v[76:79], v[148:151], v[60:63]
	ds_write_b16 v101, v88 offset:13504
	v_cvt_pk_bf16_f32 v88, v91, s0
	s_nop 1
	v_cvt_pk_bf16_f32 v76, v56, v57
	v_mfma_f32_16x16x32_bf16 v[36:39], v[72:75], v[148:151], v[36:39]
	v_cvt_pk_bf16_f32 v72, v68, v69
	v_cvt_pk_bf16_f32 v73, v70, v71
	v_cvt_pk_bf16_f32 v77, v58, v59
	ds_write_b16 v101, v92 offset:13552
	ds_write_b16 v101, v88 offset:13584
	v_cvt_pk_bf16_f32 v74, v60, v61
	v_cvt_pk_bf16_f32 v75, v62, v63
	ds_write2_b64 v99, v[72:73], v[76:77] offset1:4
	v_cvt_pk_bf16_f32 v76, v36, v37
	v_cvt_pk_bf16_f32 v77, v38, v39
	v_add_u32_e32 v72, 0x1000, v99
	ds_write2_b64 v72, v[74:75], v[76:77] offset0:32 offset1:36
	s_waitcnt lgkmcnt(0)
	s_waitcnt vmcnt(5)
	s_barrier
	ds_read_b128 v[74:77], v97 offset:13312
	v_lshl_add_u64 v[78:79], s[72:73], 0, v[106:107]
	v_lshl_add_u64 v[106:107], v[106:107], 0, s[12:13]
	s_waitcnt lgkmcnt(0)
	global_store_dwordx4 v[78:79], v[74:77], off
	s_cbranch_scc1 .LBB0_469
	s_waitcnt vmcnt(1)
	v_mov_b64_e32 v[92:93], v[16:17]
	v_mov_b64_e32 v[94:95], v[18:19]
	v_mov_b64_e32 v[88:89], v[20:21]
	v_mov_b64_e32 v[90:91], v[22:23]
	v_mov_b64_e32 v[120:121], v[104:105]
	v_mov_b64_e32 v[118:119], v[102:103]
	v_mov_b32_e32 v116, v100
	ds_read_b128 v[148:151], v200
	ds_read_b128 v[126:129], v200 offset:16384
	ds_read_b128 v[170:173], v201
	ds_read_b128 v[130:133], v201 offset:16384
	ds_read_b128 v[174:177], v202
	ds_read_b128 v[140:143], v202 offset:16384
	ds_read_b128 v[178:181], v203
	ds_read_b128 v[144:147], v203 offset:16384
	ds_read_b128 v[84:87], v208 offset:32768
	ds_read_b128 v[80:83], v208 offset:34816
	ds_read_b128 v[76:79], v209 offset:32768
	ds_read_b128 v[72:75], v209 offset:34816
	ds_read_b128 v[182:185], v124
	ds_read_b128 v[190:193], v124 offset:4352
	s_add_u32 m0, s36, 0x16800
	s_nop 0
	global_load_lds_dwordx4 v194, s[38:39]
	s_add_u32 m0, s36, 0x16c00
	s_nop 0
	global_load_lds_dwordx4 v195, s[38:39]
	s_add_u32 m0, s36, 0x1a800
	s_nop 0
	global_load_lds_dwordx4 v196, s[38:39]
	s_add_u32 m0, s36, 0x1ac00
	s_nop 0
	global_load_lds_dwordx4 v197, s[38:39]
	s_add_u32 m0, s36, 0x1e800
	s_nop 0
	global_load_lds_dwordx4 v198, s[38:39]
	s_add_u32 m0, s36, 0x1ec00
	s_nop 0
	global_load_lds_dwordx4 v199, s[38:39]
	s_add_u32 s38, s38, 0x4000
	s_addc_u32 s39, s39, 0
	v_lshl_add_u64 v[0:1], s[72:73], 0, v[110:111]
	s_mov_b32 s7, 0x23502000
	v_add_co_u32_e32 v0, vcc, s7, v0
	s_nop 1
	v_addc_co_u32_e32 v1, vcc, 0, v1, vcc
	global_load_dwordx4 v[16:19], v[0:1], off
	global_load_dwordx4 v[20:23], v[0:1], off offset:64
	v_lshl_add_u64 v[102:103], s[72:73], 0, v[108:109]
	s_mov_b32 s7, 0x1d504000
	v_add_co_u32_e32 v102, vcc, s7, v102
	s_add_u32 s8, s72, s1
	s_nop 0
	v_addc_co_u32_e32 v103, vcc, 0, v103, vcc
	s_addc_u32 s9, s73, s11
	global_load_dwordx2 v[104:105], v[102:103], off
	s_nop 0
	global_load_dwordx2 v[102:103], v[102:103], off offset:2048
	global_load_dword v100, v137, s[8:9]
	s_waitcnt lgkmcnt(1)
	v_mfma_f32_16x16x32_bf16 v[186:189], v[148:151], v[182:185], 0
	v_lshlrev_b32_e32 v134, 16, v120
	v_and_b32_e32 v135, 0xffff0000, v120
	v_lshlrev_b32_e32 v120, 16, v121
	v_mfma_f32_16x16x32_bf16 v[182:185], v[126:129], v[182:185], 0
	v_and_b32_e32 v121, 0xffff0000, v121
	v_pk_mul_f32 v[70:71], v[70:71], v[116:117] op_sel_hi:[1,0]
	v_pk_mul_f32 v[68:69], v[68:69], v[116:117] op_sel_hi:[1,0]
	s_waitcnt lgkmcnt(0)
	v_mfma_f32_16x16x32_bf16 v[148:151], v[148:151], v[190:193], 0
	v_mul_f32_e64 v58, v58, v116
	v_mul_f32_e64 v59, v59, v116
	v_pk_mul_f32 v[56:57], v[56:57], v[116:117] op_sel_hi:[1,0]
	v_pk_mul_f32 v[62:63], v[62:63], v[116:117] op_sel_hi:[1,0]
	v_mfma_f32_16x16x32_bf16 v[126:129], v[126:129], v[190:193], 0
	ds_read_b128 v[190:193], v124 offset:64
	v_pk_mul_f32 v[60:61], v[60:61], v[116:117] op_sel_hi:[1,0]
	v_pk_mul_f32 v[38:39], v[38:39], v[116:117] op_sel_hi:[1,0]
	s_waitcnt lgkmcnt(0)
	v_mfma_f32_16x16x32_bf16 v[186:189], v[170:173], v[190:193], v[186:189]
	v_mul_f32_e64 v36, v36, v116
	v_mul_f32_e64 v37, v37, v116
	s_add_i32 s6, s6, -1
	s_add_u32 s1, s1, 4
	v_mfma_f32_16x16x32_bf16 v[182:185], v[130:133], v[190:193], v[182:185]
	ds_read_b128 v[190:193], v124 offset:4416
	s_addc_u32 s11, s11, 0
	v_lshl_add_u64 v[108:109], v[108:109], 0, s[26:27]
	s_waitcnt lgkmcnt(0)
	v_mfma_f32_16x16x32_bf16 v[126:129], v[130:133], v[190:193], v[126:129]
	ds_read_b128 v[130:133], v124 offset:128
	v_lshl_add_u64 v[110:111], v[110:111], 0, s[14:15]
	v_lshl_add_u64 v[112:113], v[112:113], 0, s[26:27]
	v_mfma_f32_16x16x32_bf16 v[148:151], v[170:173], v[190:193], v[148:151]
	v_lshl_add_u64 v[114:115], v[114:115], 0, s[26:27]
	s_cmp_lg_u32 s6, 0
	s_waitcnt lgkmcnt(0)
	v_mfma_f32_16x16x32_bf16 v[170:173], v[174:177], v[130:133], v[186:189]
	v_mfma_f32_16x16x32_bf16 v[130:133], v[140:143], v[130:133], v[182:185]
	s_nop 2
	ds_read_b128 v[182:185], v124 offset:4480
	s_waitcnt lgkmcnt(0)
	v_mfma_f32_16x16x32_bf16 v[126:129], v[140:143], v[182:185], v[126:129]
	ds_read_b128 v[140:143], v124 offset:192
	s_waitcnt lgkmcnt(0)
	v_mfma_f32_16x16x32_bf16 v[170:173], v[178:181], v[140:143], v[170:173]
	v_mfma_f32_16x16x32_bf16 v[130:133], v[144:147], v[140:143], v[130:133]
	ds_read_b128 v[140:143], v124 offset:4544
	s_nop 5
	v_pk_add_f32 v[134:135], v[134:135], v[170:171] neg_lo:[0,1] neg_hi:[0,1]
	v_pk_add_f32 v[120:121], v[120:121], v[172:173] neg_lo:[0,1] neg_hi:[0,1]
	v_mfma_f32_16x16x32_bf16 v[148:151], v[174:177], v[182:185], v[148:151]
	v_cvt_pk_bf16_f32 v134, v134, v135
	v_cvt_pk_bf16_f32 v135, v120, v121
	v_lshlrev_b32_e32 v120, 16, v118
	s_waitcnt lgkmcnt(0)
	v_mfma_f32_16x16x32_bf16 v[148:151], v[178:181], v[140:143], v[148:151]
	v_and_b32_e32 v121, 0xffff0000, v118
	v_lshlrev_b32_e32 v118, 16, v119
	v_and_b32_e32 v119, 0xffff0000, v119
	ds_write_b64 v117, v[134:135] offset:8704
	v_mfma_f32_16x16x32_bf16 v[126:129], v[144:147], v[140:143], v[126:129]
	s_nop 2
	v_add_f32_e64 v120, v120, -v148
	v_add_f32_e64 v121, v121, -v149
	v_pk_add_f32 v[118:119], v[118:119], v[150:151] neg_lo:[0,1] neg_hi:[0,1]
	v_cvt_pk_bf16_f32 v120, v120, v121
	v_cvt_pk_bf16_f32 v121, v118, v119
	ds_write_b64 v117, v[120:121] offset:11008
	s_waitcnt lgkmcnt(0)
	s_barrier
	ds_read_b128 v[118:121], v122 offset:8704
	ds_read_b128 v[140:143], v123 offset:13056
	ds_read_b128 v[144:147], v122 offset:8768
	ds_read_b128 v[148:151], v123 offset:13120
	s_waitcnt lgkmcnt(3)
	v_mfma_f32_16x16x32_bf16 v[130:133], v[92:95], v[118:121], v[130:133]
	s_waitcnt lgkmcnt(2)
	v_mfma_f32_16x16x32_bf16 v[92:95], v[92:95], v[140:143], v[126:129]
	v_mfma_f32_16x16x32_bf16 v[68:71], v[84:87], v[118:121], v[68:71]
	v_mfma_f32_16x16x32_bf16 v[56:59], v[80:83], v[118:121], v[56:59]
	s_waitcnt lgkmcnt(1)
	v_mfma_f32_16x16x32_bf16 v[126:129], v[88:91], v[144:147], v[130:133]
	s_waitcnt lgkmcnt(0)
	v_mfma_f32_16x16x32_bf16 v[88:91], v[88:91], v[148:151], v[92:95]
	v_mfma_f32_16x16x32_bf16 v[60:63], v[84:87], v[140:143], v[60:63]
	s_nop 4
	v_cvt_pk_bf16_f32 v92, v126, s0
	s_nop 0
	v_cvt_pk_bf16_f32 v88, v88, s0
	ds_write_b16 v101, v92 offset:13312
	v_mfma_f32_16x16x32_bf16 v[36:39], v[80:83], v[140:143], v[36:39]
	v_cvt_pk_bf16_f32 v92, v127, s0
	ds_write_b16 v101, v88 offset:13344
	v_cvt_pk_bf16_f32 v88, v89, s0
	v_mfma_f32_16x16x32_bf16 v[68:71], v[76:79], v[144:147], v[68:71]
	ds_write_b16 v101, v92 offset:13392
	v_cvt_pk_bf16_f32 v92, v128, s0
	ds_write_b16 v101, v88 offset:13424
	v_mfma_f32_16x16x32_bf16 v[56:59], v[72:75], v[144:147], v[56:59]
	v_cvt_pk_bf16_f32 v88, v90, s0
	ds_write_b16 v101, v92 offset:13472
	v_cvt_pk_bf16_f32 v92, v129, s0
	v_mfma_f32_16x16x32_bf16 v[60:63], v[76:79], v[148:151], v[60:63]
	ds_write_b16 v101, v88 offset:13504
	v_cvt_pk_bf16_f32 v88, v91, s0
	s_nop 1
	v_cvt_pk_bf16_f32 v76, v56, v57
	v_mfma_f32_16x16x32_bf16 v[36:39], v[72:75], v[148:151], v[36:39]
	v_cvt_pk_bf16_f32 v72, v68, v69
	v_cvt_pk_bf16_f32 v73, v70, v71
	v_cvt_pk_bf16_f32 v77, v58, v59
	ds_write_b16 v101, v92 offset:13552
	ds_write_b16 v101, v88 offset:13584
	v_cvt_pk_bf16_f32 v74, v60, v61
	v_cvt_pk_bf16_f32 v75, v62, v63
	ds_write2_b64 v99, v[72:73], v[76:77] offset1:4
	v_cvt_pk_bf16_f32 v76, v36, v37
	v_cvt_pk_bf16_f32 v77, v38, v39
	v_add_u32_e32 v72, 0x1000, v99
	ds_write2_b64 v72, v[74:75], v[76:77] offset0:32 offset1:36
	s_waitcnt lgkmcnt(0)
	s_waitcnt vmcnt(5)
	s_barrier
	ds_read_b128 v[74:77], v97 offset:13312
	v_lshl_add_u64 v[78:79], s[72:73], 0, v[106:107]
	v_lshl_add_u64 v[106:107], v[106:107], 0, s[12:13]
	s_waitcnt lgkmcnt(0)
	global_store_dwordx4 v[78:79], v[74:77], off
	ds_read_b128 v[52:55], v204
	ds_read_b128 v[64:67], v204 offset:16384
	ds_read_b128 v[44:47], v205
	ds_read_b128 v[48:51], v205 offset:16384
	ds_read_b128 v[32:35], v206
	ds_read_b128 v[40:43], v206 offset:16384
	ds_read_b128 v[24:27], v207
	ds_read_b128 v[28:31], v207 offset:16384
	ds_read_b128 v[12:15], v210 offset:32768
	ds_read_b128 v[8:11], v210 offset:34816
	ds_read_b128 v[4:7], v211 offset:32768
	ds_read_b128 v[0:3], v211 offset:34816
	s_waitcnt lgkmcnt(0)
	ds_read_b128 v[74:77], v124
	ds_read_b128 v[82:85], v124 offset:4352
	s_waitcnt vmcnt(1)
	v_pk_mul_f32 v[38:39], v[100:101], v[38:39] op_sel_hi:[0,1]
	v_pk_mul_f32 v[36:37], v[100:101], v[36:37] op_sel_hi:[0,1]
	s_mov_b32 s1, s52
	s_waitcnt lgkmcnt(1)
	v_mfma_f32_16x16x32_bf16 v[78:81], v[52:55], v[74:77], 0
	v_mfma_f32_16x16x32_bf16 v[74:77], v[64:67], v[74:77], 0
	s_waitcnt lgkmcnt(0)
	v_mfma_f32_16x16x32_bf16 v[52:55], v[52:55], v[82:85], 0
	v_mfma_f32_16x16x32_bf16 v[64:67], v[64:67], v[82:85], 0
	ds_read_b128 v[82:85], v124 offset:64
	s_waitcnt lgkmcnt(0)
	v_mfma_f32_16x16x32_bf16 v[78:81], v[44:47], v[82:85], v[78:81]
	v_mfma_f32_16x16x32_bf16 v[74:77], v[48:51], v[82:85], v[74:77]
	ds_read_b128 v[82:85], v124 offset:4416
	s_waitcnt lgkmcnt(0)
	v_mfma_f32_16x16x32_bf16 v[44:47], v[44:47], v[82:85], v[52:55]
	s_nop 2
	ds_read_b128 v[52:55], v124 offset:128
	v_mfma_f32_16x16x32_bf16 v[48:51], v[48:51], v[82:85], v[64:67]
	s_waitcnt lgkmcnt(0)
	v_mfma_f32_16x16x32_bf16 v[64:67], v[32:35], v[52:55], v[78:81]
	v_mfma_f32_16x16x32_bf16 v[52:55], v[40:43], v[52:55], v[74:77]
	s_nop 2
	ds_read_b128 v[74:77], v124 offset:4480
	s_waitcnt lgkmcnt(0)
	v_mfma_f32_16x16x32_bf16 v[32:35], v[32:35], v[74:77], v[44:47]
	s_nop 2
	ds_read_b128 v[44:47], v124 offset:192
	v_mfma_f32_16x16x32_bf16 v[40:43], v[40:43], v[74:77], v[48:51]
	s_waitcnt lgkmcnt(0)
	v_mfma_f32_16x16x32_bf16 v[48:51], v[24:27], v[44:47], v[64:67]
	v_mfma_f32_16x16x32_bf16 v[44:47], v[28:31], v[44:47], v[52:55]
	s_nop 2
	ds_read_b128 v[52:55], v124 offset:4544
	s_waitcnt lgkmcnt(0)
	v_mfma_f32_16x16x32_bf16 v[24:27], v[24:27], v[52:55], v[32:35]
	s_nop 2
	v_lshlrev_b32_e32 v32, 16, v104
	v_and_b32_e32 v33, 0xffff0000, v104
	v_lshlrev_b32_e32 v34, 16, v105
	v_and_b32_e32 v35, 0xffff0000, v105
	v_pk_add_f32 v[32:33], v[32:33], v[48:49] neg_lo:[0,1] neg_hi:[0,1]
	v_pk_add_f32 v[34:35], v[34:35], v[50:51] neg_lo:[0,1] neg_hi:[0,1]
	v_cvt_pk_bf16_f32 v32, v32, v33
	v_cvt_pk_bf16_f32 v33, v34, v35
	ds_write_b64 v117, v[32:33] offset:8704
	v_lshlrev_b32_e32 v32, 16, v102
	v_and_b32_e32 v33, 0xffff0000, v102
	v_pk_add_f32 v[24:25], v[32:33], v[24:25] neg_lo:[0,1] neg_hi:[0,1]
	v_lshlrev_b32_e32 v32, 16, v103
	v_and_b32_e32 v33, 0xffff0000, v103
	v_pk_add_f32 v[26:27], v[32:33], v[26:27] neg_lo:[0,1] neg_hi:[0,1]
	v_cvt_pk_bf16_f32 v24, v24, v25
	v_cvt_pk_bf16_f32 v25, v26, v27
	ds_write_b64 v117, v[24:25] offset:11008
	v_mfma_f32_16x16x32_bf16 v[28:31], v[28:31], v[52:55], v[40:43]
	s_waitcnt lgkmcnt(0)
	s_barrier
	ds_read_b128 v[24:27], v122 offset:8704
	ds_read_b128 v[32:35], v123 offset:13056
	ds_read_b128 v[40:43], v122 offset:8768
	ds_read_b128 v[48:51], v123 offset:13120
	s_waitcnt lgkmcnt(3)
	v_mfma_f32_16x16x32_bf16 v[44:47], v[16:19], v[24:27], v[44:47]
	s_waitcnt lgkmcnt(2)
	v_mfma_f32_16x16x32_bf16 v[16:19], v[16:19], v[32:35], v[28:31]
	s_waitcnt lgkmcnt(1)
	v_mfma_f32_16x16x32_bf16 v[28:31], v[20:23], v[40:43], v[44:47]
	s_waitcnt lgkmcnt(0)
	v_mfma_f32_16x16x32_bf16 v[16:19], v[20:23], v[48:51], v[16:19]
	v_mul_f32_e64 v22, v100, v62
	v_mul_f32_e64 v23, v100, v63
	s_nop 3
	v_cvt_pk_bf16_f32 v20, v28, s0
	ds_write_b16 v101, v20 offset:13312
	v_cvt_pk_bf16_f32 v20, v29, s0
	ds_write_b16 v101, v20 offset:13392
	v_cvt_pk_bf16_f32 v16, v16, s0
	ds_write_b16 v101, v16 offset:13344
	v_cvt_pk_bf16_f32 v16, v17, s0
	v_cvt_pk_bf16_f32 v20, v30, s0
	ds_write_b16 v101, v16 offset:13424
	v_cvt_pk_bf16_f32 v16, v18, s0
	ds_write_b16 v101, v20 offset:13472
	v_cvt_pk_bf16_f32 v20, v31, s0
	ds_write_b16 v101, v16 offset:13504
	v_cvt_pk_bf16_f32 v16, v19, s0
	ds_write_b16 v101, v20 offset:13552
	ds_write_b16 v101, v16 offset:13584
	v_pk_mul_f32 v[18:19], v[100:101], v[70:71] op_sel_hi:[0,1]
	v_pk_mul_f32 v[16:17], v[100:101], v[68:69] op_sel_hi:[0,1]
	v_pk_mul_f32 v[20:21], v[100:101], v[60:61] op_sel_hi:[0,1]
	v_pk_mul_f32 v[30:31], v[100:101], v[58:59] op_sel_hi:[0,1]
	v_pk_mul_f32 v[28:29], v[100:101], v[56:57] op_sel_hi:[0,1]
	v_mfma_f32_16x16x32_bf16 v[16:19], v[12:15], v[24:27], v[16:19]
	v_mfma_f32_16x16x32_bf16 v[12:15], v[12:15], v[32:35], v[20:23]
	v_mfma_f32_16x16x32_bf16 v[20:23], v[8:11], v[24:27], v[28:31]
	v_mfma_f32_16x16x32_bf16 v[8:11], v[8:11], v[32:35], v[36:39]
	v_mfma_f32_16x16x32_bf16 v[16:19], v[4:7], v[40:43], v[16:19]
	v_mfma_f32_16x16x32_bf16 v[4:7], v[4:7], v[48:51], v[12:15]
	v_mfma_f32_16x16x32_bf16 v[12:15], v[0:3], v[40:43], v[20:23]
	v_mfma_f32_16x16x32_bf16 v[0:3], v[0:3], v[48:51], v[8:11]
	s_nop 5
	v_cvt_pk_bf16_f32 v4, v4, v5
	v_cvt_pk_bf16_f32 v5, v6, v7
	v_cvt_pk_bf16_f32 v6, v12, v13
	v_cvt_pk_bf16_f32 v8, v16, v17
	v_cvt_pk_bf16_f32 v9, v18, v19
	v_cvt_pk_bf16_f32 v7, v14, v15
	v_cvt_pk_bf16_f32 v0, v0, v1
	v_cvt_pk_bf16_f32 v1, v2, v3
	ds_write2_b64 v99, v[8:9], v[6:7] offset1:4
	ds_write2_b64 v72, v[4:5], v[0:1] offset0:32 offset1:36
	s_waitcnt lgkmcnt(0)
	s_barrier
	v_lshl_or_b32 v4, v98, 11, s4
	v_mov_b32_e32 v5, s5
	v_readlane_b32 s4, v254, 36
	ds_read_b128 v[0:3], v97 offset:13312
	v_readlane_b32 s5, v254, 37
	v_mov_b32_e32 v97, v137
	s_nop 0
	v_lshl_add_u64 v[4:5], s[4:5], 0, v[4:5]
	v_lshl_add_u64 v[4:5], v[4:5], 0, s[0:1]
	s_lshl_b32 s0, s10, 6
	v_lshl_add_u64 v[4:5], v[4:5], 0, s[0:1]
	v_lshl_add_u64 v[4:5], v[4:5], 0, v[96:97]
	s_waitcnt lgkmcnt(0)
	global_store_dwordx4 v[4:5], v[0:3], off
